# FFN-up conv+SiLU epilogue fast path: scalar v_fma/v_fmac/v_add/v_mul instead of packed-f32 ops (same per-element IEEE ops)
# baseline (speedup 1.0000x reference)
.LBB0_640:
	s_and_b64 s[2:3], s[8:9], exec
	s_waitcnt vmcnt(0)
	v_readlane_b32 s2, v255, 15
	v_readlane_b32 s4, v255, 19
	v_readlane_b32 s3, v255, 16
	v_readlane_b32 s5, v255, 20
	s_cselect_b32 s42, s2, s4
	v_readlane_b32 s2, v255, 17
	s_cselect_b32 s28, s51, 0
	s_cselect_b32 s29, s52, 0
	s_cselect_b32 s43, s3, s5
	s_cselect_b32 s46, s2, 0
	s_cmp_lt_i32 s44, 4
	s_mov_b64 s[2:3], -1
	s_waitcnt vmcnt(0) lgkmcnt(0)
	s_barrier
	s_cbranch_scc1 .LBB0_1047
	s_cmp_lt_i32 s44, 6
	s_cbranch_scc1 .LBB0_1041
	s_cmp_gt_i32 s44, 6
	s_cbranch_scc0 .LBB0_654
	s_movk_i32 s15, 0x210
	v_lshlrev_b32_e32 v0, 3, v223
	v_mul_lo_u32 v132, v225, s15
	v_cvt_pk_bf16_f32 v131, v128, v129
	v_cvt_pk_bf16_f32 v130, v126, v127
	v_add3_u32 v0, v224, v132, v0
	v_cvt_pk_bf16_f32 v133, v124, v125
	v_cvt_pk_bf16_f32 v132, v122, v123
	ds_write2_b64 v0, v[130:131], v[132:133] offset1:4
	v_cvt_pk_bf16_f32 v131, v120, v121
	v_cvt_pk_bf16_f32 v130, v118, v119
	v_cvt_pk_bf16_f32 v133, v116, v117
	v_cvt_pk_bf16_f32 v132, v114, v115
	ds_write2_b64 v0, v[130:131], v[132:133] offset0:32 offset1:36
	v_cvt_pk_bf16_f32 v131, v112, v113
	v_cvt_pk_bf16_f32 v130, v110, v111
	v_cvt_pk_bf16_f32 v133, v108, v109
	v_cvt_pk_bf16_f32 v132, v106, v107
	v_add_u32_e32 v134, 0x2000, v0
	ds_write2_b64 v134, v[130:131], v[132:133] offset0:32 offset1:36
	v_cvt_pk_bf16_f32 v131, v104, v105
	v_cvt_pk_bf16_f32 v130, v102, v103
	v_cvt_pk_bf16_f32 v133, v100, v101
	v_cvt_pk_bf16_f32 v132, v98, v99
	ds_write2_b64 v134, v[130:131], v[132:133] offset0:64 offset1:68
	v_cvt_pk_bf16_f32 v131, v96, v97
	v_cvt_pk_bf16_f32 v130, v94, v95
	v_cvt_pk_bf16_f32 v133, v92, v93
	v_cvt_pk_bf16_f32 v132, v90, v91
	v_add_u32_e32 v134, 0x4000, v0
	ds_write2_b64 v134, v[130:131], v[132:133] offset0:64 offset1:68
	v_cvt_pk_bf16_f32 v131, v88, v89
	v_cvt_pk_bf16_f32 v130, v86, v87
	v_cvt_pk_bf16_f32 v133, v84, v85
	v_cvt_pk_bf16_f32 v132, v82, v83
	ds_write2_b64 v134, v[130:131], v[132:133] offset0:96 offset1:100
	v_cvt_pk_bf16_f32 v131, v80, v81
	v_cvt_pk_bf16_f32 v130, v78, v79
	v_cvt_pk_bf16_f32 v133, v76, v77
	v_cvt_pk_bf16_f32 v132, v74, v75
	v_add_u32_e32 v134, 0x6000, v0
	ds_write2_b64 v134, v[130:131], v[132:133] offset0:96 offset1:100
	v_cvt_pk_bf16_f32 v131, v72, v73
	v_cvt_pk_bf16_f32 v130, v70, v71
	v_cvt_pk_bf16_f32 v133, v68, v69
	v_cvt_pk_bf16_f32 v132, v66, v67
	ds_write2_b64 v134, v[130:131], v[132:133] offset0:128 offset1:132
	v_cvt_pk_bf16_f32 v131, v64, v65
	v_cvt_pk_bf16_f32 v130, v62, v63
	v_cvt_pk_bf16_f32 v133, v60, v61
	v_cvt_pk_bf16_f32 v132, v58, v59
	v_add_u32_e32 v134, 0x8000, v0
	ds_write2_b64 v134, v[130:131], v[132:133] offset0:128 offset1:132
	v_cvt_pk_bf16_f32 v131, v56, v57
	v_cvt_pk_bf16_f32 v130, v54, v55
	v_cvt_pk_bf16_f32 v133, v52, v53
	v_cvt_pk_bf16_f32 v132, v50, v51
	ds_write2_b64 v134, v[130:131], v[132:133] offset0:160 offset1:164
	v_cvt_pk_bf16_f32 v131, v48, v49
	v_cvt_pk_bf16_f32 v130, v46, v47
	v_cvt_pk_bf16_f32 v133, v44, v45
	v_cvt_pk_bf16_f32 v132, v42, v43
	v_add_u32_e32 v134, 0xa000, v0
	ds_write2_b64 v134, v[130:131], v[132:133] offset0:160 offset1:164
	v_cvt_pk_bf16_f32 v131, v36, v37
	v_cvt_pk_bf16_f32 v130, v34, v35
	v_cvt_pk_bf16_f32 v133, v32, v33
	v_cvt_pk_bf16_f32 v132, v30, v31
	ds_write2_b64 v134, v[130:131], v[132:133] offset0:192 offset1:196
	v_cvt_pk_bf16_f32 v131, v40, v41
	v_cvt_pk_bf16_f32 v130, v38, v39
	v_cvt_pk_bf16_f32 v133, v28, v29
	v_cvt_pk_bf16_f32 v132, v26, v27
	v_add_u32_e32 v134, 0xc000, v0
	ds_write2_b64 v134, v[130:131], v[132:133] offset0:192 offset1:196
	v_cvt_pk_bf16_f32 v131, v24, v25
	v_cvt_pk_bf16_f32 v130, v22, v23
	v_cvt_pk_bf16_f32 v133, v20, v21
	v_cvt_pk_bf16_f32 v132, v18, v19
	ds_write2_b64 v134, v[130:131], v[132:133] offset0:224 offset1:228
	v_cvt_pk_bf16_f32 v131, v16, v17
	v_cvt_pk_bf16_f32 v130, v14, v15
	v_cvt_pk_bf16_f32 v133, v12, v13
	v_cvt_pk_bf16_f32 v132, v10, v11
	v_add_u32_e32 v134, 0xe000, v0
	ds_write2_b64 v134, v[130:131], v[132:133] offset0:224 offset1:228
	v_cvt_pk_bf16_f32 v131, v8, v9
	v_cvt_pk_bf16_f32 v130, v6, v7
	v_cvt_pk_bf16_f32 v133, v4, v5
	v_cvt_pk_bf16_f32 v132, v2, v3
	v_add_u32_e32 v0, 0xe800, v0
	ds_write2_b64 v0, v[130:131], v[132:133] offset1:4
	v_lshlrev_b32_e32 v0, 2, v175
	v_and_b32_e32 v0, 0x7c, v0
	s_mul_i32 s2, s28, 0x10800
	v_readlane_b32 s48, v253, 61
	v_lshl_or_b32 v164, s47, 7, v0
	s_mul_hi_u32 s3, s28, 0x10800
	v_readlane_b32 s49, v253, 62
	s_add_u32 s2, s48, s2
	v_ashrrev_i32_e32 v165, 31, v164
	s_addc_u32 s3, s49, s3
	v_lshlrev_b64 v[130:131], 2, v[164:165]
	v_lshl_add_u64 v[150:151], s[2:3], 0, v[130:131]
	s_movk_i32 s2, 0x5000
	v_add_co_u32_e32 v134, vcc, s2, v150
	s_mov_b32 s2, 0xb000
	s_nop 0
	v_addc_co_u32_e32 v135, vcc, 0, v151, vcc
	v_add_co_u32_e32 v138, vcc, s2, v150
	v_readlane_b32 s50, v253, 63
	s_nop 0
	v_addc_co_u32_e32 v139, vcc, 0, v151, vcc
	v_add_co_u32_e32 v142, vcc, s25, v150
	s_mul_i32 s4, s28, 0x5800
	s_nop 0
	v_addc_co_u32_e32 v143, vcc, 0, v151, vcc
	s_mov_b32 s2, 0x8000
	v_readlane_b32 s51, v254, 0
	s_mul_hi_u32 s5, s28, 0x5800
	s_add_u32 s4, s50, s4
	v_add_co_u32_e32 v146, vcc, s2, v150
	s_addc_u32 s5, s51, s5
	s_nop 0
	v_addc_co_u32_e32 v147, vcc, 0, v151, vcc
	s_mov_b32 s2, 0xd000
	s_waitcnt lgkmcnt(0)
	s_barrier
	v_lshl_add_u64 v[158:159], s[4:5], 0, v[130:131]
	global_load_dwordx4 v[130:133], v[150:151], off
	v_add_co_u32_e32 v150, vcc, s2, v150
	global_load_dwordx4 v[134:137], v[134:135], off offset:2048
	s_nop 0
	global_load_dwordx4 v[138:141], v[138:139], off
	v_addc_co_u32_e32 v151, vcc, 0, v151, vcc
	global_load_dwordx4 v[142:145], v[142:143], off offset:3072
	s_nop 0
	global_load_dwordx4 v[146:149], v[146:147], off offset:1024
	s_nop 0
	global_load_dwordx4 v[150:153], v[150:151], off offset:3072
	s_nop 0
	global_load_dwordx4 v[154:157], v[158:159], off
	v_add_co_u32_e32 v158, vcc, 0x2000, v158
	v_ashrrev_i32_e32 v0, 5, v175
	s_nop 0
	v_addc_co_u32_e32 v159, vcc, 0, v159, vcc
	global_load_dwordx4 v[158:161], v[158:159], off offset:3072
	v_readlane_b32 s2, v252, 32
	v_readlane_b32 s3, v252, 33
	v_mul_lo_u32 v166, v0, s15
	v_and_b32_e32 v167, 31, v175
	s_mov_b32 s14, 0
	v_lshl_add_u64 v[164:165], v[164:165], 1, s[2:3]
	v_lshl_add_u32 v166, v167, 3, v166
	v_add_u32_e32 v167, s40, v0
	s_waitcnt vmcnt(0)
	s_mov_b32 s14, 0x8800
	v_mul_u32_u24_e32 v63, 0x2100, v0
	v_and_b32_e32 v64, 31, v175
	v_lshl_add_u32 v63, v64, 3, v63
	v_lshlrev_b32_e32 v61, 4, v0
	v_add_u32_e32 v61, 1, v61
	v_add_u32_e32 v62, s40, v61
	s_mov_b32 s4, 0x78787879
	v_mul_hi_i32 v60, v62, s4
	v_lshrrev_b32_e32 v64, 31, v60
	v_ashrrev_i32_e32 v60, 11, v60
	v_add_u32_e32 v60, v60, v64
	v_mul_i32_i24_e32 v60, 0x1100, v60
	v_sub_u32_e32 v60, v62, v60
	s_movk_i32 s4, 0x1600
	v_mad_i64_i32 v[58:59], s[4:5], v62, s4, v[164:165]
	v_mov_b32_e32 v56, 0x1600
	v_mov_b32_e32 v57, 0
	ds_read2_b64 v[26:29], v63 offset1:32
	ds_read2_b64 v[68:71], v63 offset0:66 offset1:98
	s_waitcnt lgkmcnt(0)
	v_lshlrev_b32_e32 v2, 16, v26
	v_and_b32_e32 v3, 0xffff0000, v26
	v_lshlrev_b32_e32 v4, 16, v27
	v_and_b32_e32 v5, 0xffff0000, v27
	v_lshlrev_b32_e32 v14, 16, v28
	v_and_b32_e32 v15, 0xffff0000, v28
	v_lshlrev_b32_e32 v16, 16, v29
	v_and_b32_e32 v17, 0xffff0000, v29
	v_lshlrev_b32_e32 v6, 16, v68
	v_and_b32_e32 v7, 0xffff0000, v68
	v_lshlrev_b32_e32 v8, 16, v69
	v_and_b32_e32 v9, 0xffff0000, v69
	v_lshlrev_b32_e32 v18, 16, v70
	v_and_b32_e32 v19, 0xffff0000, v70
	v_lshlrev_b32_e32 v20, 16, v71
	v_and_b32_e32 v21, 0xffff0000, v71
	v_add_u32_e32 v63, 0x420, v63
	v_add_u32_e32 v64, -1, v60
	v_add_u32_e32 v65, 0xfffffeff, v60
	v_cmp_gt_u32_e32 vcc, 0xfef, v65
	s_mov_b64 s[4:5], vcc
	v_cmp_gt_u32_e32 vcc, 0xef, v64
	s_or_b64 s[4:5], s[4:5], vcc
	v_add_u32_e32 v64, 15, v62
	v_cmp_gt_i32_e32 vcc, s14, v64
	s_and_b64 s[4:5], s[4:5], vcc
	s_xor_b64 s[4:5], s[4:5], exec
	s_cmp_eq_u64 s[4:5], 0
	s_cbranch_scc0 .Lconv_slow
	v_cmp_gt_u32_e32 vcc, 15, v0
	ds_read2_b64 v[26:29], v63 offset1:32
	s_waitcnt lgkmcnt(0)
	v_lshlrev_b32_e32 v10, 16, v26
	v_and_b32_e32 v11, 0xffff0000, v26
	v_lshlrev_b32_e32 v12, 16, v27
	v_and_b32_e32 v13, 0xffff0000, v27
	v_lshlrev_b32_e32 v22, 16, v28
	v_and_b32_e32 v23, 0xffff0000, v28
	v_lshlrev_b32_e32 v24, 16, v29
	v_and_b32_e32 v25, 0xffff0000, v29
	v_add_u32_e32 v63, 0x210, v63
	ds_read2_b64 v[26:29], v63 offset1:32
	v_fma_f32 v30, v146, v18, v158
	v_fma_f32 v31, v147, v19, v159
	v_fma_f32 v32, v148, v20, v160
	v_fma_f32 v33, v149, v21, v161
	v_fma_f32 v34, v134, v6, v154
	v_fma_f32 v35, v135, v7, v155
	v_fma_f32 v36, v136, v8, v156
	v_fma_f32 v37, v137, v9, v157
	v_fmac_f32_e32 v30, v142, v14
	v_fmac_f32_e32 v31, v143, v15
	v_fmac_f32_e32 v32, v144, v16
	v_fmac_f32_e32 v33, v145, v17
	v_fmac_f32_e32 v34, v130, v2
	v_fmac_f32_e32 v35, v131, v3
	v_fmac_f32_e32 v36, v132, v4
	v_fmac_f32_e32 v37, v133, v5
	v_fmac_f32_e32 v30, v150, v22
	v_fmac_f32_e32 v31, v151, v23
	v_fmac_f32_e32 v32, v152, v24
	v_fmac_f32_e32 v33, v153, v25
	v_fmac_f32_e32 v34, v138, v10
	v_fmac_f32_e32 v35, v139, v11
	v_fmac_f32_e32 v36, v140, v12
	v_fmac_f32_e32 v37, v141, v13
	v_mul_f32_e32 v42, 0xbfb8aa3b, v30
	v_mul_f32_e32 v43, 0xbfb8aa3b, v31
	v_mul_f32_e32 v44, 0xbfb8aa3b, v32
	v_mul_f32_e32 v45, 0xbfb8aa3b, v33
	v_exp_f32_e32 v42, v42
	v_exp_f32_e32 v43, v43
	v_exp_f32_e32 v44, v44
	v_exp_f32_e32 v45, v45
	v_add_f32_e32 v42, 1.0, v42
	v_add_f32_e32 v43, 1.0, v43
	v_add_f32_e32 v44, 1.0, v44
	v_add_f32_e32 v45, 1.0, v45
	v_rcp_f32_e32 v46, v42
	v_rcp_f32_e32 v47, v43
	v_rcp_f32_e32 v48, v44
	v_rcp_f32_e32 v49, v45
	v_mul_f32_e32 v46, v30, v46
	v_mul_f32_e32 v47, v31, v47
	v_mul_f32_e32 v48, v32, v48
	v_mul_f32_e32 v49, v33, v49
	v_mul_f32_e32 v34, v34, v46
	v_mul_f32_e32 v35, v35, v47
	v_mul_f32_e32 v36, v36, v48
	v_mul_f32_e32 v37, v37, v49
	v_cvt_pk_bf16_f32 v66, v34, v35
	v_cvt_pk_bf16_f32 v67, v36, v37
	global_store_dwordx2 v[58:59], v[66:67], off
	v_lshl_add_u64 v[58:59], v[58:59], 0, v[56:57]
	s_waitcnt lgkmcnt(0)
	v_lshlrev_b32_e32 v2, 16, v26
	v_and_b32_e32 v3, 0xffff0000, v26
	v_lshlrev_b32_e32 v4, 16, v27
	v_and_b32_e32 v5, 0xffff0000, v27
	v_lshlrev_b32_e32 v14, 16, v28
	v_and_b32_e32 v15, 0xffff0000, v28
	v_lshlrev_b32_e32 v16, 16, v29
	v_and_b32_e32 v17, 0xffff0000, v29
	v_add_u32_e32 v63, 0x210, v63
	ds_read2_b64 v[26:29], v63 offset1:32
	v_fma_f32 v30, v146, v22, v158
	v_fma_f32 v31, v147, v23, v159
	v_fma_f32 v32, v148, v24, v160
	v_fma_f32 v33, v149, v25, v161
	v_fma_f32 v34, v134, v10, v154
	v_fma_f32 v35, v135, v11, v155
	v_fma_f32 v36, v136, v12, v156
	v_fma_f32 v37, v137, v13, v157
	v_fmac_f32_e32 v30, v142, v18
	v_fmac_f32_e32 v31, v143, v19
	v_fmac_f32_e32 v32, v144, v20
	v_fmac_f32_e32 v33, v145, v21
	v_fmac_f32_e32 v34, v130, v6
	v_fmac_f32_e32 v35, v131, v7
	v_fmac_f32_e32 v36, v132, v8
	v_fmac_f32_e32 v37, v133, v9
	v_fmac_f32_e32 v30, v150, v14
	v_fmac_f32_e32 v31, v151, v15
	v_fmac_f32_e32 v32, v152, v16
	v_fmac_f32_e32 v33, v153, v17
	v_fmac_f32_e32 v34, v138, v2
	v_fmac_f32_e32 v35, v139, v3
	v_fmac_f32_e32 v36, v140, v4
	v_fmac_f32_e32 v37, v141, v5
	v_mul_f32_e32 v42, 0xbfb8aa3b, v30
	v_mul_f32_e32 v43, 0xbfb8aa3b, v31
	v_mul_f32_e32 v44, 0xbfb8aa3b, v32
	v_mul_f32_e32 v45, 0xbfb8aa3b, v33
	v_exp_f32_e32 v42, v42
	v_exp_f32_e32 v43, v43
	v_exp_f32_e32 v44, v44
	v_exp_f32_e32 v45, v45
	v_add_f32_e32 v42, 1.0, v42
	v_add_f32_e32 v43, 1.0, v43
	v_add_f32_e32 v44, 1.0, v44
	v_add_f32_e32 v45, 1.0, v45
	v_rcp_f32_e32 v46, v42
	v_rcp_f32_e32 v47, v43
	v_rcp_f32_e32 v48, v44
	v_rcp_f32_e32 v49, v45
	v_mul_f32_e32 v46, v30, v46
	v_mul_f32_e32 v47, v31, v47
	v_mul_f32_e32 v48, v32, v48
	v_mul_f32_e32 v49, v33, v49
	v_mul_f32_e32 v34, v34, v46
	v_mul_f32_e32 v35, v35, v47
	v_mul_f32_e32 v36, v36, v48
	v_mul_f32_e32 v37, v37, v49
	v_cvt_pk_bf16_f32 v66, v34, v35
	v_cvt_pk_bf16_f32 v67, v36, v37
	global_store_dwordx2 v[58:59], v[66:67], off
	v_lshl_add_u64 v[58:59], v[58:59], 0, v[56:57]
	s_waitcnt lgkmcnt(0)
	v_lshlrev_b32_e32 v6, 16, v26
	v_and_b32_e32 v7, 0xffff0000, v26
	v_lshlrev_b32_e32 v8, 16, v27
	v_and_b32_e32 v9, 0xffff0000, v27
	v_lshlrev_b32_e32 v18, 16, v28
	v_and_b32_e32 v19, 0xffff0000, v28
	v_lshlrev_b32_e32 v20, 16, v29
	v_and_b32_e32 v21, 0xffff0000, v29
	v_add_u32_e32 v63, 0x210, v63
	ds_read2_b64 v[26:29], v63 offset1:32
	v_fma_f32 v30, v146, v14, v158
	v_fma_f32 v31, v147, v15, v159
	v_fma_f32 v32, v148, v16, v160
	v_fma_f32 v33, v149, v17, v161
	v_fma_f32 v34, v134, v2, v154
	v_fma_f32 v35, v135, v3, v155
	v_fma_f32 v36, v136, v4, v156
	v_fma_f32 v37, v137, v5, v157
	v_fmac_f32_e32 v30, v142, v22
	v_fmac_f32_e32 v31, v143, v23
	v_fmac_f32_e32 v32, v144, v24
	v_fmac_f32_e32 v33, v145, v25
	v_fmac_f32_e32 v34, v130, v10
	v_fmac_f32_e32 v35, v131, v11
	v_fmac_f32_e32 v36, v132, v12
	v_fmac_f32_e32 v37, v133, v13
	v_fmac_f32_e32 v30, v150, v18
	v_fmac_f32_e32 v31, v151, v19
	v_fmac_f32_e32 v32, v152, v20
	v_fmac_f32_e32 v33, v153, v21
	v_fmac_f32_e32 v34, v138, v6
	v_fmac_f32_e32 v35, v139, v7
	v_fmac_f32_e32 v36, v140, v8
	v_fmac_f32_e32 v37, v141, v9
	v_mul_f32_e32 v42, 0xbfb8aa3b, v30
	v_mul_f32_e32 v43, 0xbfb8aa3b, v31
	v_mul_f32_e32 v44, 0xbfb8aa3b, v32
	v_mul_f32_e32 v45, 0xbfb8aa3b, v33
	v_exp_f32_e32 v42, v42
	v_exp_f32_e32 v43, v43
	v_exp_f32_e32 v44, v44
	v_exp_f32_e32 v45, v45
	v_add_f32_e32 v42, 1.0, v42
	v_add_f32_e32 v43, 1.0, v43
	v_add_f32_e32 v44, 1.0, v44
	v_add_f32_e32 v45, 1.0, v45
	v_rcp_f32_e32 v46, v42
	v_rcp_f32_e32 v47, v43
	v_rcp_f32_e32 v48, v44
	v_rcp_f32_e32 v49, v45
	v_mul_f32_e32 v46, v30, v46
	v_mul_f32_e32 v47, v31, v47
	v_mul_f32_e32 v48, v32, v48
	v_mul_f32_e32 v49, v33, v49
	v_mul_f32_e32 v34, v34, v46
	v_mul_f32_e32 v35, v35, v47
	v_mul_f32_e32 v36, v36, v48
	v_mul_f32_e32 v37, v37, v49
	v_cvt_pk_bf16_f32 v66, v34, v35
	v_cvt_pk_bf16_f32 v67, v36, v37
	global_store_dwordx2 v[58:59], v[66:67], off
	v_lshl_add_u64 v[58:59], v[58:59], 0, v[56:57]
	s_waitcnt lgkmcnt(0)
	v_lshlrev_b32_e32 v10, 16, v26
	v_and_b32_e32 v11, 0xffff0000, v26
	v_lshlrev_b32_e32 v12, 16, v27
	v_and_b32_e32 v13, 0xffff0000, v27
	v_lshlrev_b32_e32 v22, 16, v28
	v_and_b32_e32 v23, 0xffff0000, v28
	v_lshlrev_b32_e32 v24, 16, v29
	v_and_b32_e32 v25, 0xffff0000, v29
	v_add_u32_e32 v63, 0x210, v63
	ds_read2_b64 v[26:29], v63 offset1:32
	v_fma_f32 v30, v146, v18, v158
	v_fma_f32 v31, v147, v19, v159
	v_fma_f32 v32, v148, v20, v160
	v_fma_f32 v33, v149, v21, v161
	v_fma_f32 v34, v134, v6, v154
	v_fma_f32 v35, v135, v7, v155
	v_fma_f32 v36, v136, v8, v156
	v_fma_f32 v37, v137, v9, v157
	v_fmac_f32_e32 v30, v142, v14
	v_fmac_f32_e32 v31, v143, v15
	v_fmac_f32_e32 v32, v144, v16
	v_fmac_f32_e32 v33, v145, v17
	v_fmac_f32_e32 v34, v130, v2
	v_fmac_f32_e32 v35, v131, v3
	v_fmac_f32_e32 v36, v132, v4
	v_fmac_f32_e32 v37, v133, v5
	v_fmac_f32_e32 v30, v150, v22
	v_fmac_f32_e32 v31, v151, v23
	v_fmac_f32_e32 v32, v152, v24
	v_fmac_f32_e32 v33, v153, v25
	v_fmac_f32_e32 v34, v138, v10
	v_fmac_f32_e32 v35, v139, v11
	v_fmac_f32_e32 v36, v140, v12
	v_fmac_f32_e32 v37, v141, v13
	v_mul_f32_e32 v42, 0xbfb8aa3b, v30
	v_mul_f32_e32 v43, 0xbfb8aa3b, v31
	v_mul_f32_e32 v44, 0xbfb8aa3b, v32
	v_mul_f32_e32 v45, 0xbfb8aa3b, v33
	v_exp_f32_e32 v42, v42
	v_exp_f32_e32 v43, v43
	v_exp_f32_e32 v44, v44
	v_exp_f32_e32 v45, v45
	v_add_f32_e32 v42, 1.0, v42
	v_add_f32_e32 v43, 1.0, v43
	v_add_f32_e32 v44, 1.0, v44
	v_add_f32_e32 v45, 1.0, v45
	v_rcp_f32_e32 v46, v42
	v_rcp_f32_e32 v47, v43
	v_rcp_f32_e32 v48, v44
	v_rcp_f32_e32 v49, v45
	v_mul_f32_e32 v46, v30, v46
	v_mul_f32_e32 v47, v31, v47
	v_mul_f32_e32 v48, v32, v48
	v_mul_f32_e32 v49, v33, v49
	v_mul_f32_e32 v34, v34, v46
	v_mul_f32_e32 v35, v35, v47
	v_mul_f32_e32 v36, v36, v48
	v_mul_f32_e32 v37, v37, v49
	v_cvt_pk_bf16_f32 v66, v34, v35
	v_cvt_pk_bf16_f32 v67, v36, v37
	global_store_dwordx2 v[58:59], v[66:67], off
	v_lshl_add_u64 v[58:59], v[58:59], 0, v[56:57]
	s_waitcnt lgkmcnt(0)
	v_lshlrev_b32_e32 v2, 16, v26
	v_and_b32_e32 v3, 0xffff0000, v26
	v_lshlrev_b32_e32 v4, 16, v27
	v_and_b32_e32 v5, 0xffff0000, v27
	v_lshlrev_b32_e32 v14, 16, v28
	v_and_b32_e32 v15, 0xffff0000, v28
	v_lshlrev_b32_e32 v16, 16, v29
	v_and_b32_e32 v17, 0xffff0000, v29
	v_add_u32_e32 v63, 0x210, v63
	ds_read2_b64 v[26:29], v63 offset1:32
	v_fma_f32 v30, v146, v22, v158
	v_fma_f32 v31, v147, v23, v159
	v_fma_f32 v32, v148, v24, v160
	v_fma_f32 v33, v149, v25, v161
	v_fma_f32 v34, v134, v10, v154
	v_fma_f32 v35, v135, v11, v155
	v_fma_f32 v36, v136, v12, v156
	v_fma_f32 v37, v137, v13, v157
	v_fmac_f32_e32 v30, v142, v18
	v_fmac_f32_e32 v31, v143, v19
	v_fmac_f32_e32 v32, v144, v20
	v_fmac_f32_e32 v33, v145, v21
	v_fmac_f32_e32 v34, v130, v6
	v_fmac_f32_e32 v35, v131, v7
	v_fmac_f32_e32 v36, v132, v8
	v_fmac_f32_e32 v37, v133, v9
	v_fmac_f32_e32 v30, v150, v14
	v_fmac_f32_e32 v31, v151, v15
	v_fmac_f32_e32 v32, v152, v16
	v_fmac_f32_e32 v33, v153, v17
	v_fmac_f32_e32 v34, v138, v2
	v_fmac_f32_e32 v35, v139, v3
	v_fmac_f32_e32 v36, v140, v4
	v_fmac_f32_e32 v37, v141, v5
	v_mul_f32_e32 v42, 0xbfb8aa3b, v30
	v_mul_f32_e32 v43, 0xbfb8aa3b, v31
	v_mul_f32_e32 v44, 0xbfb8aa3b, v32
	v_mul_f32_e32 v45, 0xbfb8aa3b, v33
	v_exp_f32_e32 v42, v42
	v_exp_f32_e32 v43, v43
	v_exp_f32_e32 v44, v44
	v_exp_f32_e32 v45, v45
	v_add_f32_e32 v42, 1.0, v42
	v_add_f32_e32 v43, 1.0, v43
	v_add_f32_e32 v44, 1.0, v44
	v_add_f32_e32 v45, 1.0, v45
	v_rcp_f32_e32 v46, v42
	v_rcp_f32_e32 v47, v43
	v_rcp_f32_e32 v48, v44
	v_rcp_f32_e32 v49, v45
	v_mul_f32_e32 v46, v30, v46
	v_mul_f32_e32 v47, v31, v47
	v_mul_f32_e32 v48, v32, v48
	v_mul_f32_e32 v49, v33, v49
	v_mul_f32_e32 v34, v34, v46
	v_mul_f32_e32 v35, v35, v47
	v_mul_f32_e32 v36, v36, v48
	v_mul_f32_e32 v37, v37, v49
	v_cvt_pk_bf16_f32 v66, v34, v35
	v_cvt_pk_bf16_f32 v67, v36, v37
	global_store_dwordx2 v[58:59], v[66:67], off
	v_lshl_add_u64 v[58:59], v[58:59], 0, v[56:57]
	s_waitcnt lgkmcnt(0)
	v_lshlrev_b32_e32 v6, 16, v26
	v_and_b32_e32 v7, 0xffff0000, v26
	v_lshlrev_b32_e32 v8, 16, v27
	v_and_b32_e32 v9, 0xffff0000, v27
	v_lshlrev_b32_e32 v18, 16, v28
	v_and_b32_e32 v19, 0xffff0000, v28
	v_lshlrev_b32_e32 v20, 16, v29
	v_and_b32_e32 v21, 0xffff0000, v29
	v_add_u32_e32 v63, 0x210, v63
	ds_read2_b64 v[26:29], v63 offset1:32
	v_fma_f32 v30, v146, v14, v158
	v_fma_f32 v31, v147, v15, v159
	v_fma_f32 v32, v148, v16, v160
	v_fma_f32 v33, v149, v17, v161
	v_fma_f32 v34, v134, v2, v154
	v_fma_f32 v35, v135, v3, v155
	v_fma_f32 v36, v136, v4, v156
	v_fma_f32 v37, v137, v5, v157
	v_fmac_f32_e32 v30, v142, v22
	v_fmac_f32_e32 v31, v143, v23
	v_fmac_f32_e32 v32, v144, v24
	v_fmac_f32_e32 v33, v145, v25
	v_fmac_f32_e32 v34, v130, v10
	v_fmac_f32_e32 v35, v131, v11
	v_fmac_f32_e32 v36, v132, v12
	v_fmac_f32_e32 v37, v133, v13
	v_fmac_f32_e32 v30, v150, v18
	v_fmac_f32_e32 v31, v151, v19
	v_fmac_f32_e32 v32, v152, v20
	v_fmac_f32_e32 v33, v153, v21
	v_fmac_f32_e32 v34, v138, v6
	v_fmac_f32_e32 v35, v139, v7
	v_fmac_f32_e32 v36, v140, v8
	v_fmac_f32_e32 v37, v141, v9
	v_mul_f32_e32 v42, 0xbfb8aa3b, v30
	v_mul_f32_e32 v43, 0xbfb8aa3b, v31
	v_mul_f32_e32 v44, 0xbfb8aa3b, v32
	v_mul_f32_e32 v45, 0xbfb8aa3b, v33
	v_exp_f32_e32 v42, v42
	v_exp_f32_e32 v43, v43
	v_exp_f32_e32 v44, v44
	v_exp_f32_e32 v45, v45
	v_add_f32_e32 v42, 1.0, v42
	v_add_f32_e32 v43, 1.0, v43
	v_add_f32_e32 v44, 1.0, v44
	v_add_f32_e32 v45, 1.0, v45
	v_rcp_f32_e32 v46, v42
	v_rcp_f32_e32 v47, v43
	v_rcp_f32_e32 v48, v44
	v_rcp_f32_e32 v49, v45
	v_mul_f32_e32 v46, v30, v46
	v_mul_f32_e32 v47, v31, v47
	v_mul_f32_e32 v48, v32, v48
	v_mul_f32_e32 v49, v33, v49
	v_mul_f32_e32 v34, v34, v46
	v_mul_f32_e32 v35, v35, v47
	v_mul_f32_e32 v36, v36, v48
	v_mul_f32_e32 v37, v37, v49
	v_cvt_pk_bf16_f32 v66, v34, v35
	v_cvt_pk_bf16_f32 v67, v36, v37
	global_store_dwordx2 v[58:59], v[66:67], off
	v_lshl_add_u64 v[58:59], v[58:59], 0, v[56:57]
	s_waitcnt lgkmcnt(0)
	v_lshlrev_b32_e32 v10, 16, v26
	v_and_b32_e32 v11, 0xffff0000, v26
	v_lshlrev_b32_e32 v12, 16, v27
	v_and_b32_e32 v13, 0xffff0000, v27
	v_lshlrev_b32_e32 v22, 16, v28
	v_and_b32_e32 v23, 0xffff0000, v28
	v_lshlrev_b32_e32 v24, 16, v29
	v_and_b32_e32 v25, 0xffff0000, v29
	v_add_u32_e32 v63, 0x210, v63
	ds_read2_b64 v[26:29], v63 offset1:32
	v_fma_f32 v30, v146, v18, v158
	v_fma_f32 v31, v147, v19, v159
	v_fma_f32 v32, v148, v20, v160
	v_fma_f32 v33, v149, v21, v161
	v_fma_f32 v34, v134, v6, v154
	v_fma_f32 v35, v135, v7, v155
	v_fma_f32 v36, v136, v8, v156
	v_fma_f32 v37, v137, v9, v157
	v_fmac_f32_e32 v30, v142, v14
	v_fmac_f32_e32 v31, v143, v15
	v_fmac_f32_e32 v32, v144, v16
	v_fmac_f32_e32 v33, v145, v17
	v_fmac_f32_e32 v34, v130, v2
	v_fmac_f32_e32 v35, v131, v3
	v_fmac_f32_e32 v36, v132, v4
	v_fmac_f32_e32 v37, v133, v5
	v_fmac_f32_e32 v30, v150, v22
	v_fmac_f32_e32 v31, v151, v23
	v_fmac_f32_e32 v32, v152, v24
	v_fmac_f32_e32 v33, v153, v25
	v_fmac_f32_e32 v34, v138, v10
	v_fmac_f32_e32 v35, v139, v11
	v_fmac_f32_e32 v36, v140, v12
	v_fmac_f32_e32 v37, v141, v13
	v_mul_f32_e32 v42, 0xbfb8aa3b, v30
	v_mul_f32_e32 v43, 0xbfb8aa3b, v31
	v_mul_f32_e32 v44, 0xbfb8aa3b, v32
	v_mul_f32_e32 v45, 0xbfb8aa3b, v33
	v_exp_f32_e32 v42, v42
	v_exp_f32_e32 v43, v43
	v_exp_f32_e32 v44, v44
	v_exp_f32_e32 v45, v45
	v_add_f32_e32 v42, 1.0, v42
	v_add_f32_e32 v43, 1.0, v43
	v_add_f32_e32 v44, 1.0, v44
	v_add_f32_e32 v45, 1.0, v45
	v_rcp_f32_e32 v46, v42
	v_rcp_f32_e32 v47, v43
	v_rcp_f32_e32 v48, v44
	v_rcp_f32_e32 v49, v45
	v_mul_f32_e32 v46, v30, v46
	v_mul_f32_e32 v47, v31, v47
	v_mul_f32_e32 v48, v32, v48
	v_mul_f32_e32 v49, v33, v49
	v_mul_f32_e32 v34, v34, v46
	v_mul_f32_e32 v35, v35, v47
	v_mul_f32_e32 v36, v36, v48
	v_mul_f32_e32 v37, v37, v49
	v_cvt_pk_bf16_f32 v66, v34, v35
	v_cvt_pk_bf16_f32 v67, v36, v37
	global_store_dwordx2 v[58:59], v[66:67], off
	v_lshl_add_u64 v[58:59], v[58:59], 0, v[56:57]
	s_waitcnt lgkmcnt(0)
	v_lshlrev_b32_e32 v2, 16, v26
	v_and_b32_e32 v3, 0xffff0000, v26
	v_lshlrev_b32_e32 v4, 16, v27
	v_and_b32_e32 v5, 0xffff0000, v27
	v_lshlrev_b32_e32 v14, 16, v28
	v_and_b32_e32 v15, 0xffff0000, v28
	v_lshlrev_b32_e32 v16, 16, v29
	v_and_b32_e32 v17, 0xffff0000, v29
	v_add_u32_e32 v63, 0x210, v63
	ds_read2_b64 v[26:29], v63 offset1:32
	v_fma_f32 v30, v146, v22, v158
	v_fma_f32 v31, v147, v23, v159
	v_fma_f32 v32, v148, v24, v160
	v_fma_f32 v33, v149, v25, v161
	v_fma_f32 v34, v134, v10, v154
	v_fma_f32 v35, v135, v11, v155
	v_fma_f32 v36, v136, v12, v156
	v_fma_f32 v37, v137, v13, v157
	v_fmac_f32_e32 v30, v142, v18
	v_fmac_f32_e32 v31, v143, v19
	v_fmac_f32_e32 v32, v144, v20
	v_fmac_f32_e32 v33, v145, v21
	v_fmac_f32_e32 v34, v130, v6
	v_fmac_f32_e32 v35, v131, v7
	v_fmac_f32_e32 v36, v132, v8
	v_fmac_f32_e32 v37, v133, v9
	v_fmac_f32_e32 v30, v150, v14
	v_fmac_f32_e32 v31, v151, v15
	v_fmac_f32_e32 v32, v152, v16
	v_fmac_f32_e32 v33, v153, v17
	v_fmac_f32_e32 v34, v138, v2
	v_fmac_f32_e32 v35, v139, v3
	v_fmac_f32_e32 v36, v140, v4
	v_fmac_f32_e32 v37, v141, v5
	v_mul_f32_e32 v42, 0xbfb8aa3b, v30
	v_mul_f32_e32 v43, 0xbfb8aa3b, v31
	v_mul_f32_e32 v44, 0xbfb8aa3b, v32
	v_mul_f32_e32 v45, 0xbfb8aa3b, v33
	v_exp_f32_e32 v42, v42
	v_exp_f32_e32 v43, v43
	v_exp_f32_e32 v44, v44
	v_exp_f32_e32 v45, v45
	v_add_f32_e32 v42, 1.0, v42
	v_add_f32_e32 v43, 1.0, v43
	v_add_f32_e32 v44, 1.0, v44
	v_add_f32_e32 v45, 1.0, v45
	v_rcp_f32_e32 v46, v42
	v_rcp_f32_e32 v47, v43
	v_rcp_f32_e32 v48, v44
	v_rcp_f32_e32 v49, v45
	v_mul_f32_e32 v46, v30, v46
	v_mul_f32_e32 v47, v31, v47
	v_mul_f32_e32 v48, v32, v48
	v_mul_f32_e32 v49, v33, v49
	v_mul_f32_e32 v34, v34, v46
	v_mul_f32_e32 v35, v35, v47
	v_mul_f32_e32 v36, v36, v48
	v_mul_f32_e32 v37, v37, v49
	v_cvt_pk_bf16_f32 v66, v34, v35
	v_cvt_pk_bf16_f32 v67, v36, v37
	global_store_dwordx2 v[58:59], v[66:67], off
	v_lshl_add_u64 v[58:59], v[58:59], 0, v[56:57]
	s_waitcnt lgkmcnt(0)
	v_lshlrev_b32_e32 v6, 16, v26
	v_and_b32_e32 v7, 0xffff0000, v26
	v_lshlrev_b32_e32 v8, 16, v27
	v_and_b32_e32 v9, 0xffff0000, v27
	v_lshlrev_b32_e32 v18, 16, v28
	v_and_b32_e32 v19, 0xffff0000, v28
	v_lshlrev_b32_e32 v20, 16, v29
	v_and_b32_e32 v21, 0xffff0000, v29
	v_add_u32_e32 v63, 0x210, v63
	ds_read2_b64 v[26:29], v63 offset1:32
	v_fma_f32 v30, v146, v14, v158
	v_fma_f32 v31, v147, v15, v159
	v_fma_f32 v32, v148, v16, v160
	v_fma_f32 v33, v149, v17, v161
	v_fma_f32 v34, v134, v2, v154
	v_fma_f32 v35, v135, v3, v155
	v_fma_f32 v36, v136, v4, v156
	v_fma_f32 v37, v137, v5, v157
	v_fmac_f32_e32 v30, v142, v22
	v_fmac_f32_e32 v31, v143, v23
	v_fmac_f32_e32 v32, v144, v24
	v_fmac_f32_e32 v33, v145, v25
	v_fmac_f32_e32 v34, v130, v10
	v_fmac_f32_e32 v35, v131, v11
	v_fmac_f32_e32 v36, v132, v12
	v_fmac_f32_e32 v37, v133, v13
	v_fmac_f32_e32 v30, v150, v18
	v_fmac_f32_e32 v31, v151, v19
	v_fmac_f32_e32 v32, v152, v20
	v_fmac_f32_e32 v33, v153, v21
	v_fmac_f32_e32 v34, v138, v6
	v_fmac_f32_e32 v35, v139, v7
	v_fmac_f32_e32 v36, v140, v8
	v_fmac_f32_e32 v37, v141, v9
	v_mul_f32_e32 v42, 0xbfb8aa3b, v30
	v_mul_f32_e32 v43, 0xbfb8aa3b, v31
	v_mul_f32_e32 v44, 0xbfb8aa3b, v32
	v_mul_f32_e32 v45, 0xbfb8aa3b, v33
	v_exp_f32_e32 v42, v42
	v_exp_f32_e32 v43, v43
	v_exp_f32_e32 v44, v44
	v_exp_f32_e32 v45, v45
	v_add_f32_e32 v42, 1.0, v42
	v_add_f32_e32 v43, 1.0, v43
	v_add_f32_e32 v44, 1.0, v44
	v_add_f32_e32 v45, 1.0, v45
	v_rcp_f32_e32 v46, v42
	v_rcp_f32_e32 v47, v43
	v_rcp_f32_e32 v48, v44
	v_rcp_f32_e32 v49, v45
	v_mul_f32_e32 v46, v30, v46
	v_mul_f32_e32 v47, v31, v47
	v_mul_f32_e32 v48, v32, v48
	v_mul_f32_e32 v49, v33, v49
	v_mul_f32_e32 v34, v34, v46
	v_mul_f32_e32 v35, v35, v47
	v_mul_f32_e32 v36, v36, v48
	v_mul_f32_e32 v37, v37, v49
	v_cvt_pk_bf16_f32 v66, v34, v35
	v_cvt_pk_bf16_f32 v67, v36, v37
	global_store_dwordx2 v[58:59], v[66:67], off
	v_lshl_add_u64 v[58:59], v[58:59], 0, v[56:57]
	s_waitcnt lgkmcnt(0)
	v_lshlrev_b32_e32 v10, 16, v26
	v_and_b32_e32 v11, 0xffff0000, v26
	v_lshlrev_b32_e32 v12, 16, v27
	v_and_b32_e32 v13, 0xffff0000, v27
	v_lshlrev_b32_e32 v22, 16, v28
	v_and_b32_e32 v23, 0xffff0000, v28
	v_lshlrev_b32_e32 v24, 16, v29
	v_and_b32_e32 v25, 0xffff0000, v29
	v_add_u32_e32 v63, 0x210, v63
	ds_read2_b64 v[26:29], v63 offset1:32
	v_fma_f32 v30, v146, v18, v158
	v_fma_f32 v31, v147, v19, v159
	v_fma_f32 v32, v148, v20, v160
	v_fma_f32 v33, v149, v21, v161
	v_fma_f32 v34, v134, v6, v154
	v_fma_f32 v35, v135, v7, v155
	v_fma_f32 v36, v136, v8, v156
	v_fma_f32 v37, v137, v9, v157
	v_fmac_f32_e32 v30, v142, v14
	v_fmac_f32_e32 v31, v143, v15
	v_fmac_f32_e32 v32, v144, v16
	v_fmac_f32_e32 v33, v145, v17
	v_fmac_f32_e32 v34, v130, v2
	v_fmac_f32_e32 v35, v131, v3
	v_fmac_f32_e32 v36, v132, v4
	v_fmac_f32_e32 v37, v133, v5
	v_fmac_f32_e32 v30, v150, v22
	v_fmac_f32_e32 v31, v151, v23
	v_fmac_f32_e32 v32, v152, v24
	v_fmac_f32_e32 v33, v153, v25
	v_fmac_f32_e32 v34, v138, v10
	v_fmac_f32_e32 v35, v139, v11
	v_fmac_f32_e32 v36, v140, v12
	v_fmac_f32_e32 v37, v141, v13
	v_mul_f32_e32 v42, 0xbfb8aa3b, v30
	v_mul_f32_e32 v43, 0xbfb8aa3b, v31
	v_mul_f32_e32 v44, 0xbfb8aa3b, v32
	v_mul_f32_e32 v45, 0xbfb8aa3b, v33
	v_exp_f32_e32 v42, v42
	v_exp_f32_e32 v43, v43
	v_exp_f32_e32 v44, v44
	v_exp_f32_e32 v45, v45
	v_add_f32_e32 v42, 1.0, v42
	v_add_f32_e32 v43, 1.0, v43
	v_add_f32_e32 v44, 1.0, v44
	v_add_f32_e32 v45, 1.0, v45
	v_rcp_f32_e32 v46, v42
	v_rcp_f32_e32 v47, v43
	v_rcp_f32_e32 v48, v44
	v_rcp_f32_e32 v49, v45
	v_mul_f32_e32 v46, v30, v46
	v_mul_f32_e32 v47, v31, v47
	v_mul_f32_e32 v48, v32, v48
	v_mul_f32_e32 v49, v33, v49
	v_mul_f32_e32 v34, v34, v46
	v_mul_f32_e32 v35, v35, v47
	v_mul_f32_e32 v36, v36, v48
	v_mul_f32_e32 v37, v37, v49
	v_cvt_pk_bf16_f32 v66, v34, v35
	v_cvt_pk_bf16_f32 v67, v36, v37
	global_store_dwordx2 v[58:59], v[66:67], off
	v_lshl_add_u64 v[58:59], v[58:59], 0, v[56:57]
	s_waitcnt lgkmcnt(0)
	v_lshlrev_b32_e32 v2, 16, v26
	v_and_b32_e32 v3, 0xffff0000, v26
	v_lshlrev_b32_e32 v4, 16, v27
	v_and_b32_e32 v5, 0xffff0000, v27
	v_lshlrev_b32_e32 v14, 16, v28
	v_and_b32_e32 v15, 0xffff0000, v28
	v_lshlrev_b32_e32 v16, 16, v29
	v_and_b32_e32 v17, 0xffff0000, v29
	v_add_u32_e32 v63, 0x210, v63
	ds_read2_b64 v[26:29], v63 offset1:32
	v_fma_f32 v30, v146, v22, v158
	v_fma_f32 v31, v147, v23, v159
	v_fma_f32 v32, v148, v24, v160
	v_fma_f32 v33, v149, v25, v161
	v_fma_f32 v34, v134, v10, v154
	v_fma_f32 v35, v135, v11, v155
	v_fma_f32 v36, v136, v12, v156
	v_fma_f32 v37, v137, v13, v157
	v_fmac_f32_e32 v30, v142, v18
	v_fmac_f32_e32 v31, v143, v19
	v_fmac_f32_e32 v32, v144, v20
	v_fmac_f32_e32 v33, v145, v21
	v_fmac_f32_e32 v34, v130, v6
	v_fmac_f32_e32 v35, v131, v7
	v_fmac_f32_e32 v36, v132, v8
	v_fmac_f32_e32 v37, v133, v9
	v_fmac_f32_e32 v30, v150, v14
	v_fmac_f32_e32 v31, v151, v15
	v_fmac_f32_e32 v32, v152, v16
	v_fmac_f32_e32 v33, v153, v17
	v_fmac_f32_e32 v34, v138, v2
	v_fmac_f32_e32 v35, v139, v3
	v_fmac_f32_e32 v36, v140, v4
	v_fmac_f32_e32 v37, v141, v5
	v_mul_f32_e32 v42, 0xbfb8aa3b, v30
	v_mul_f32_e32 v43, 0xbfb8aa3b, v31
	v_mul_f32_e32 v44, 0xbfb8aa3b, v32
	v_mul_f32_e32 v45, 0xbfb8aa3b, v33
	v_exp_f32_e32 v42, v42
	v_exp_f32_e32 v43, v43
	v_exp_f32_e32 v44, v44
	v_exp_f32_e32 v45, v45
	v_add_f32_e32 v42, 1.0, v42
	v_add_f32_e32 v43, 1.0, v43
	v_add_f32_e32 v44, 1.0, v44
	v_add_f32_e32 v45, 1.0, v45
	v_rcp_f32_e32 v46, v42
	v_rcp_f32_e32 v47, v43
	v_rcp_f32_e32 v48, v44
	v_rcp_f32_e32 v49, v45
	v_mul_f32_e32 v46, v30, v46
	v_mul_f32_e32 v47, v31, v47
	v_mul_f32_e32 v48, v32, v48
	v_mul_f32_e32 v49, v33, v49
	v_mul_f32_e32 v34, v34, v46
	v_mul_f32_e32 v35, v35, v47
	v_mul_f32_e32 v36, v36, v48
	v_mul_f32_e32 v37, v37, v49
	v_cvt_pk_bf16_f32 v66, v34, v35
	v_cvt_pk_bf16_f32 v67, v36, v37
	global_store_dwordx2 v[58:59], v[66:67], off
	v_lshl_add_u64 v[58:59], v[58:59], 0, v[56:57]
	s_waitcnt lgkmcnt(0)
	v_lshlrev_b32_e32 v6, 16, v26
	v_and_b32_e32 v7, 0xffff0000, v26
	v_lshlrev_b32_e32 v8, 16, v27
	v_and_b32_e32 v9, 0xffff0000, v27
	v_lshlrev_b32_e32 v18, 16, v28
	v_and_b32_e32 v19, 0xffff0000, v28
	v_lshlrev_b32_e32 v20, 16, v29
	v_and_b32_e32 v21, 0xffff0000, v29
	v_add_u32_e32 v63, 0x210, v63
	ds_read2_b64 v[26:29], v63 offset1:32
	v_fma_f32 v30, v146, v14, v158
	v_fma_f32 v31, v147, v15, v159
	v_fma_f32 v32, v148, v16, v160
	v_fma_f32 v33, v149, v17, v161
	v_fma_f32 v34, v134, v2, v154
	v_fma_f32 v35, v135, v3, v155
	v_fma_f32 v36, v136, v4, v156
	v_fma_f32 v37, v137, v5, v157
	v_fmac_f32_e32 v30, v142, v22
	v_fmac_f32_e32 v31, v143, v23
	v_fmac_f32_e32 v32, v144, v24
	v_fmac_f32_e32 v33, v145, v25
	v_fmac_f32_e32 v34, v130, v10
	v_fmac_f32_e32 v35, v131, v11
	v_fmac_f32_e32 v36, v132, v12
	v_fmac_f32_e32 v37, v133, v13
	v_fmac_f32_e32 v30, v150, v18
	v_fmac_f32_e32 v31, v151, v19
	v_fmac_f32_e32 v32, v152, v20
	v_fmac_f32_e32 v33, v153, v21
	v_fmac_f32_e32 v34, v138, v6
	v_fmac_f32_e32 v35, v139, v7
	v_fmac_f32_e32 v36, v140, v8
	v_fmac_f32_e32 v37, v141, v9
	v_mul_f32_e32 v42, 0xbfb8aa3b, v30
	v_mul_f32_e32 v43, 0xbfb8aa3b, v31
	v_mul_f32_e32 v44, 0xbfb8aa3b, v32
	v_mul_f32_e32 v45, 0xbfb8aa3b, v33
	v_exp_f32_e32 v42, v42
	v_exp_f32_e32 v43, v43
	v_exp_f32_e32 v44, v44
	v_exp_f32_e32 v45, v45
	v_add_f32_e32 v42, 1.0, v42
	v_add_f32_e32 v43, 1.0, v43
	v_add_f32_e32 v44, 1.0, v44
	v_add_f32_e32 v45, 1.0, v45
	v_rcp_f32_e32 v46, v42
	v_rcp_f32_e32 v47, v43
	v_rcp_f32_e32 v48, v44
	v_rcp_f32_e32 v49, v45
	v_mul_f32_e32 v46, v30, v46
	v_mul_f32_e32 v47, v31, v47
	v_mul_f32_e32 v48, v32, v48
	v_mul_f32_e32 v49, v33, v49
	v_mul_f32_e32 v34, v34, v46
	v_mul_f32_e32 v35, v35, v47
	v_mul_f32_e32 v36, v36, v48
	v_mul_f32_e32 v37, v37, v49
	v_cvt_pk_bf16_f32 v66, v34, v35
	v_cvt_pk_bf16_f32 v67, v36, v37
	global_store_dwordx2 v[58:59], v[66:67], off
	v_lshl_add_u64 v[58:59], v[58:59], 0, v[56:57]
	s_waitcnt lgkmcnt(0)
	v_lshlrev_b32_e32 v10, 16, v26
	v_and_b32_e32 v11, 0xffff0000, v26
	v_lshlrev_b32_e32 v12, 16, v27
	v_and_b32_e32 v13, 0xffff0000, v27
	v_lshlrev_b32_e32 v22, 16, v28
	v_and_b32_e32 v23, 0xffff0000, v28
	v_lshlrev_b32_e32 v24, 16, v29
	v_and_b32_e32 v25, 0xffff0000, v29
	v_add_u32_e32 v63, 0x210, v63
	ds_read2_b64 v[26:29], v63 offset1:32
	v_fma_f32 v30, v146, v18, v158
	v_fma_f32 v31, v147, v19, v159
	v_fma_f32 v32, v148, v20, v160
	v_fma_f32 v33, v149, v21, v161
	v_fma_f32 v34, v134, v6, v154
	v_fma_f32 v35, v135, v7, v155
	v_fma_f32 v36, v136, v8, v156
	v_fma_f32 v37, v137, v9, v157
	v_fmac_f32_e32 v30, v142, v14
	v_fmac_f32_e32 v31, v143, v15
	v_fmac_f32_e32 v32, v144, v16
	v_fmac_f32_e32 v33, v145, v17
	v_fmac_f32_e32 v34, v130, v2
	v_fmac_f32_e32 v35, v131, v3
	v_fmac_f32_e32 v36, v132, v4
	v_fmac_f32_e32 v37, v133, v5
	v_fmac_f32_e32 v30, v150, v22
	v_fmac_f32_e32 v31, v151, v23
	v_fmac_f32_e32 v32, v152, v24
	v_fmac_f32_e32 v33, v153, v25
	v_fmac_f32_e32 v34, v138, v10
	v_fmac_f32_e32 v35, v139, v11
	v_fmac_f32_e32 v36, v140, v12
	v_fmac_f32_e32 v37, v141, v13
	v_mul_f32_e32 v42, 0xbfb8aa3b, v30
	v_mul_f32_e32 v43, 0xbfb8aa3b, v31
	v_mul_f32_e32 v44, 0xbfb8aa3b, v32
	v_mul_f32_e32 v45, 0xbfb8aa3b, v33
	v_exp_f32_e32 v42, v42
	v_exp_f32_e32 v43, v43
	v_exp_f32_e32 v44, v44
	v_exp_f32_e32 v45, v45
	v_add_f32_e32 v42, 1.0, v42
	v_add_f32_e32 v43, 1.0, v43
	v_add_f32_e32 v44, 1.0, v44
	v_add_f32_e32 v45, 1.0, v45
	v_rcp_f32_e32 v46, v42
	v_rcp_f32_e32 v47, v43
	v_rcp_f32_e32 v48, v44
	v_rcp_f32_e32 v49, v45
	v_mul_f32_e32 v46, v30, v46
	v_mul_f32_e32 v47, v31, v47
	v_mul_f32_e32 v48, v32, v48
	v_mul_f32_e32 v49, v33, v49
	v_mul_f32_e32 v34, v34, v46
	v_mul_f32_e32 v35, v35, v47
	v_mul_f32_e32 v36, v36, v48
	v_mul_f32_e32 v37, v37, v49
	v_cvt_pk_bf16_f32 v66, v34, v35
	v_cvt_pk_bf16_f32 v67, v36, v37
	global_store_dwordx2 v[58:59], v[66:67], off
	v_lshl_add_u64 v[58:59], v[58:59], 0, v[56:57]
	s_waitcnt lgkmcnt(0)
	v_lshlrev_b32_e32 v2, 16, v26
	v_and_b32_e32 v3, 0xffff0000, v26
	v_lshlrev_b32_e32 v4, 16, v27
	v_and_b32_e32 v5, 0xffff0000, v27
	v_lshlrev_b32_e32 v14, 16, v28
	v_and_b32_e32 v15, 0xffff0000, v28
	v_lshlrev_b32_e32 v16, 16, v29
	v_and_b32_e32 v17, 0xffff0000, v29
	v_add_u32_e32 v63, 0x210, v63
	ds_read2_b64 v[26:29], v63 offset1:32
	v_fma_f32 v30, v146, v22, v158
	v_fma_f32 v31, v147, v23, v159
	v_fma_f32 v32, v148, v24, v160
	v_fma_f32 v33, v149, v25, v161
	v_fma_f32 v34, v134, v10, v154
	v_fma_f32 v35, v135, v11, v155
	v_fma_f32 v36, v136, v12, v156
	v_fma_f32 v37, v137, v13, v157
	v_fmac_f32_e32 v30, v142, v18
	v_fmac_f32_e32 v31, v143, v19
	v_fmac_f32_e32 v32, v144, v20
	v_fmac_f32_e32 v33, v145, v21
	v_fmac_f32_e32 v34, v130, v6
	v_fmac_f32_e32 v35, v131, v7
	v_fmac_f32_e32 v36, v132, v8
	v_fmac_f32_e32 v37, v133, v9
	v_fmac_f32_e32 v30, v150, v14
	v_fmac_f32_e32 v31, v151, v15
	v_fmac_f32_e32 v32, v152, v16
	v_fmac_f32_e32 v33, v153, v17
	v_fmac_f32_e32 v34, v138, v2
	v_fmac_f32_e32 v35, v139, v3
	v_fmac_f32_e32 v36, v140, v4
	v_fmac_f32_e32 v37, v141, v5
	v_mul_f32_e32 v42, 0xbfb8aa3b, v30
	v_mul_f32_e32 v43, 0xbfb8aa3b, v31
	v_mul_f32_e32 v44, 0xbfb8aa3b, v32
	v_mul_f32_e32 v45, 0xbfb8aa3b, v33
	v_exp_f32_e32 v42, v42
	v_exp_f32_e32 v43, v43
	v_exp_f32_e32 v44, v44
	v_exp_f32_e32 v45, v45
	v_add_f32_e32 v42, 1.0, v42
	v_add_f32_e32 v43, 1.0, v43
	v_add_f32_e32 v44, 1.0, v44
	v_add_f32_e32 v45, 1.0, v45
	v_rcp_f32_e32 v46, v42
	v_rcp_f32_e32 v47, v43
	v_rcp_f32_e32 v48, v44
	v_rcp_f32_e32 v49, v45
	v_mul_f32_e32 v46, v30, v46
	v_mul_f32_e32 v47, v31, v47
	v_mul_f32_e32 v48, v32, v48
	v_mul_f32_e32 v49, v33, v49
	v_mul_f32_e32 v34, v34, v46
	v_mul_f32_e32 v35, v35, v47
	v_mul_f32_e32 v36, v36, v48
	v_mul_f32_e32 v37, v37, v49
	v_cvt_pk_bf16_f32 v66, v34, v35
	v_cvt_pk_bf16_f32 v67, v36, v37
	global_store_dwordx2 v[58:59], v[66:67], off
	v_lshl_add_u64 v[58:59], v[58:59], 0, v[56:57]
	s_waitcnt lgkmcnt(0)
	v_lshlrev_b32_e32 v6, 16, v26
	v_and_b32_e32 v7, 0xffff0000, v26
	v_lshlrev_b32_e32 v8, 16, v27
	v_and_b32_e32 v9, 0xffff0000, v27
	v_lshlrev_b32_e32 v18, 16, v28
	v_and_b32_e32 v19, 0xffff0000, v28
	v_lshlrev_b32_e32 v20, 16, v29
	v_and_b32_e32 v21, 0xffff0000, v29
	v_add_u32_e32 v63, 0x210, v63
	ds_read2_b64 v[26:29], v63 offset1:32
	v_fma_f32 v30, v146, v14, v158
	v_fma_f32 v31, v147, v15, v159
	v_fma_f32 v32, v148, v16, v160
	v_fma_f32 v33, v149, v17, v161
	v_fma_f32 v34, v134, v2, v154
	v_fma_f32 v35, v135, v3, v155
	v_fma_f32 v36, v136, v4, v156
	v_fma_f32 v37, v137, v5, v157
	v_fmac_f32_e32 v30, v142, v22
	v_fmac_f32_e32 v31, v143, v23
	v_fmac_f32_e32 v32, v144, v24
	v_fmac_f32_e32 v33, v145, v25
	v_fmac_f32_e32 v34, v130, v10
	v_fmac_f32_e32 v35, v131, v11
	v_fmac_f32_e32 v36, v132, v12
	v_fmac_f32_e32 v37, v133, v13
	v_fmac_f32_e32 v30, v150, v18
	v_fmac_f32_e32 v31, v151, v19
	v_fmac_f32_e32 v32, v152, v20
	v_fmac_f32_e32 v33, v153, v21
	v_fmac_f32_e32 v34, v138, v6
	v_fmac_f32_e32 v35, v139, v7
	v_fmac_f32_e32 v36, v140, v8
	v_fmac_f32_e32 v37, v141, v9
	v_mul_f32_e32 v42, 0xbfb8aa3b, v30
	v_mul_f32_e32 v43, 0xbfb8aa3b, v31
	v_mul_f32_e32 v44, 0xbfb8aa3b, v32
	v_mul_f32_e32 v45, 0xbfb8aa3b, v33
	v_exp_f32_e32 v42, v42
	v_exp_f32_e32 v43, v43
	v_exp_f32_e32 v44, v44
	v_exp_f32_e32 v45, v45
	v_add_f32_e32 v42, 1.0, v42
	v_add_f32_e32 v43, 1.0, v43
	v_add_f32_e32 v44, 1.0, v44
	v_add_f32_e32 v45, 1.0, v45
	v_rcp_f32_e32 v46, v42
	v_rcp_f32_e32 v47, v43
	v_rcp_f32_e32 v48, v44
	v_rcp_f32_e32 v49, v45
	v_mul_f32_e32 v46, v30, v46
	v_mul_f32_e32 v47, v31, v47
	v_mul_f32_e32 v48, v32, v48
	v_mul_f32_e32 v49, v33, v49
	v_mul_f32_e32 v34, v34, v46
	v_mul_f32_e32 v35, v35, v47
	v_mul_f32_e32 v36, v36, v48
	v_mul_f32_e32 v37, v37, v49
	v_cvt_pk_bf16_f32 v66, v34, v35
	v_cvt_pk_bf16_f32 v67, v36, v37
	s_and_saveexec_b64 s[4:5], vcc
	global_store_dwordx2 v[58:59], v[66:67], off
	s_or_b64 exec, exec, s[4:5]
	v_lshl_add_u64 v[58:59], v[58:59], 0, v[56:57]
	s_waitcnt lgkmcnt(0)
	v_lshlrev_b32_e32 v10, 16, v26
	v_and_b32_e32 v11, 0xffff0000, v26
	v_lshlrev_b32_e32 v12, 16, v27
	v_and_b32_e32 v13, 0xffff0000, v27
	v_lshlrev_b32_e32 v22, 16, v28
	v_and_b32_e32 v23, 0xffff0000, v28
	v_lshlrev_b32_e32 v24, 16, v29
	v_and_b32_e32 v25, 0xffff0000, v29
	v_fma_f32 v30, v146, v18, v158
	v_fma_f32 v31, v147, v19, v159
	v_fma_f32 v32, v148, v20, v160
	v_fma_f32 v33, v149, v21, v161
	v_fma_f32 v34, v134, v6, v154
	v_fma_f32 v35, v135, v7, v155
	v_fma_f32 v36, v136, v8, v156
	v_fma_f32 v37, v137, v9, v157
	v_fmac_f32_e32 v30, v142, v14
	v_fmac_f32_e32 v31, v143, v15
	v_fmac_f32_e32 v32, v144, v16
	v_fmac_f32_e32 v33, v145, v17
	v_fmac_f32_e32 v34, v130, v2
	v_fmac_f32_e32 v35, v131, v3
	v_fmac_f32_e32 v36, v132, v4
	v_fmac_f32_e32 v37, v133, v5
	v_fmac_f32_e32 v30, v150, v22
	v_fmac_f32_e32 v31, v151, v23
	v_fmac_f32_e32 v32, v152, v24
	v_fmac_f32_e32 v33, v153, v25
	v_fmac_f32_e32 v34, v138, v10
	v_fmac_f32_e32 v35, v139, v11
	v_fmac_f32_e32 v36, v140, v12
	v_fmac_f32_e32 v37, v141, v13
	v_mul_f32_e32 v42, 0xbfb8aa3b, v30
	v_mul_f32_e32 v43, 0xbfb8aa3b, v31
	v_mul_f32_e32 v44, 0xbfb8aa3b, v32
	v_mul_f32_e32 v45, 0xbfb8aa3b, v33
	v_exp_f32_e32 v42, v42
	v_exp_f32_e32 v43, v43
	v_exp_f32_e32 v44, v44
	v_exp_f32_e32 v45, v45
	v_add_f32_e32 v42, 1.0, v42
	v_add_f32_e32 v43, 1.0, v43
	v_add_f32_e32 v44, 1.0, v44
	v_add_f32_e32 v45, 1.0, v45
	v_rcp_f32_e32 v46, v42
	v_rcp_f32_e32 v47, v43
	v_rcp_f32_e32 v48, v44
	v_rcp_f32_e32 v49, v45
	v_mul_f32_e32 v46, v30, v46
	v_mul_f32_e32 v47, v31, v47
	v_mul_f32_e32 v48, v32, v48
	v_mul_f32_e32 v49, v33, v49
	v_mul_f32_e32 v34, v34, v46
	v_mul_f32_e32 v35, v35, v47
	v_mul_f32_e32 v36, v36, v48
	v_mul_f32_e32 v37, v37, v49
	v_cvt_pk_bf16_f32 v66, v34, v35
	v_cvt_pk_bf16_f32 v67, v36, v37
	s_and_saveexec_b64 s[4:5], vcc
	global_store_dwordx2 v[58:59], v[66:67], off
	s_or_b64 exec, exec, s[4:5]
	v_lshl_add_u64 v[58:59], v[58:59], 0, v[56:57]
	s_branch .Lconv_done
